# baseline (speedup 1.0000x reference)
; __device__ __forceinline__ size_t kv_row(int row, int head) { const int S = row < NPROMPT ? S_P : S_S, sb = row & ~(S - 1); return (size_t)sb * 16 + (size_t)head * S + (row - sb); }
; __global__ void __launch_bounds__(512) fwd_megakernel(Args args) {
;     ...
;                     int sh, qb, sb, S_;
;                     if (pass == 0) { sh = U >> 5; qb = U & 31; S_ = S_S; sb = NPROMPT + (sh >> 4) * S_S; } else { sh = U >> 3; qb = U & 7; S_ = S_P; sb = (sh >> 4) * S_P; }
;                     const int head = sh & 15, tok = sb + qb * 512 + 64 * wave + r;
;                     bf16_t* qrow_a = Q1 + (size_t)tok * 1536 + head * 96; bf16_t* qrow_b = qrow_a + (size_t)32 * 1536;
;                     bf16x8 qfa[6], qfb[6];
;                     mla_load_q(qrow_a, h, tok_pos(tok), qn, ropeC_c, ropeC_s, qfa);
;                     mla_load_q(qrow_b, h, tok_pos(tok + 32), qn, ropeC_c, ropeC_s, qfb);
;                     att::attn_unit64<96>(al, qfa, qfb, K1 + kv_row(sb, head) * 96, 96, V1 + kv_row(sb, head) * 64, 64, 0, S_ / 64, qrow_a, 32 * 1536);
.LBB0_1120:
	s_lshl_b32 s1, s20, 9
	s_add_i32 s1, s1, s18
	s_and_b32 s0, s19, 15
	v_add_u32_e32 v20, s1, v208
	v_mov_b64_e32 v[0:1], s[68:69]
	v_mad_i64_i32 v[0:1], s[20:21], v20, s28, v[0:1]
	s_mul_i32 s4, s0, 0xc0
	v_lshl_add_u64 v[162:163], v[0:1], 0, s[4:5]
	v_mov_b32_e32 v159, v161
	v_lshl_add_u64 v[164:165], v[162:163], 0, s[6:7]
	v_lshl_add_u64 v[16:17], v[162:163], 0, v[158:159]
	v_lshl_add_u64 v[18:19], v[164:165], 0, v[158:159]
	global_load_dwordx4 v[40:43], v[16:17], off offset:128
	global_load_dwordx4 v[44:47], v[16:17], off offset:160
	global_load_dwordx4 v[64:67], v[16:17], off offset:96
	global_load_dwordx4 v[68:71], v[18:19], off offset:128
	global_load_dwordx4 v[72:75], v[18:19], off offset:160
	global_load_dwordx4 v[76:79], v[18:19], off offset:96
	global_load_dwordx4 v[96:99], v[16:17], off offset:64
	global_load_dwordx4 v[100:103], v[18:19], off offset:64
	global_load_dwordx4 v[8:11], v[156:157], off offset:272
	global_load_dwordx4 v[12:15], v[156:157], off offset:256
	global_load_dwordx4 v[0:3], v[156:157], off offset:336
	global_load_dwordx4 v[4:7], v[156:157], off offset:320
	global_load_dwordx4 v[32:35], v[156:157], off offset:208
	global_load_dwordx4 v[36:39], v[156:157], off offset:192
	global_load_dwordx4 v[104:107], v[16:17], off
	global_load_dwordx4 v[166:169], v[16:17], off offset:32
	global_load_dwordx4 v[80:83], v[18:19], off
	global_load_dwordx4 v[188:191], v[18:19], off offset:32
	s_cmpk_lt_i32 s18, 0x4000
	s_cselect_b32 s1, 0xfffff000, s27
	v_cmp_lt_i32_e32 vcc, s30, v20
	s_cselect_b32 s4, 12, 14
	s_and_b32 s20, s1, s18
	v_cndmask_b32_e32 v21, v210, v211, vcc
	v_cmp_lt_i32_e32 vcc, s31, v20
	s_ashr_i32 s21, s20, 31
	s_mov_b32 s1, s5
	v_add_u32_e32 v22, 32, v20
	v_cndmask_b32_e32 v23, v210, v211, vcc
	s_lshl_b64 s[22:23], s[20:21], 4
	s_lshl_b64 s[0:1], s[0:1], s4
	v_and_b32_e32 v20, v21, v20
	v_and_b32_e32 v21, v23, v22
	s_add_u32 s0, s22, s0
	v_lshl_or_b32 v20, v20, 6, v207
	v_lshl_or_b32 v28, v21, 6, v207
	s_addc_u32 s1, s23, s1
	s_sub_i32 s4, s18, s20
	global_load_dwordx4 v[56:59], v20, s[96:97] offset:16
	global_load_dwordx4 v[48:51], v20, s[96:97]
	global_load_dwordx4 v[60:63], v20, s[84:85] offset:16
	global_load_dwordx4 v[52:55], v20, s[84:85]
	global_load_dwordx4 v[16:19], v28, s[96:97] offset:16
	global_load_dwordx4 v[24:27], v28, s[96:97]
	s_nop 0
	global_load_dwordx4 v[20:23], v28, s[84:85] offset:16
	s_nop 0
	global_load_dwordx4 v[28:31], v28, s[84:85]
	s_ashr_i32 s18, s4, 31
	s_add_u32 s20, s0, s4
	s_addc_u32 s21, s1, s18
	s_mul_i32 s0, s21, 0xc0
	s_mul_hi_u32 s1, s20, 0xc0
	s_add_i32 s1, s1, s0
	s_mul_i32 s0, s20, 0xc0
	s_add_u32 s18, s8, s0
	s_addc_u32 s19, s9, s1
	v_lshlrev_b32_e32 v251, 4, v206
	global_load_dwordx4 v[248:251], v251, s[18:19]
	s_lshl_b64 s[98:99], s[20:21], 7
	s_add_u32 s98, s12, s98
	s_addc_u32 s99, s13, s99
	v_lshlrev_b32_e32 v255, 4, v206
	global_load_dwordx4 v[252:255], v255, s[98:99]
	v_mov_b32_e32 v243, 0x2000
	v_lshl_add_u32 v243, v206, 4, v243
	global_load_dwordx4 v[240:243], v243, s[18:19]
	s_waitcnt vmcnt(22)
	v_lshlrev_b32_e32 v88, 16, v71
	v_and_b32_e32 v89, 0xffff0000, v71
	s_waitcnt vmcnt(21)
	v_lshlrev_b32_e32 v84, 16, v75
	s_waitcnt vmcnt(19)
	v_lshlrev_b32_e32 v180, 16, v96
	v_and_b32_e32 v181, 0xffff0000, v96
	v_lshlrev_b32_e32 v178, 16, v97
	v_and_b32_e32 v179, 0xffff0000, v97
	v_lshlrev_b32_e32 v174, 16, v98
	s_waitcnt vmcnt(11)
	v_and_b32_e32 v199, 0xffff0000, v104
	v_lshlrev_b32_e32 v198, 16, v104
	v_mul_f32_e32 v96, v199, v199
	v_lshlrev_b32_e32 v200, 16, v105
	v_and_b32_e32 v201, 0xffff0000, v105
	v_pk_fma_f32 v[96:97], v[198:199], v[198:199], v[96:97] op_sel_hi:[1,1,0]
	v_and_b32_e32 v175, 0xffff0000, v98
	v_pk_fma_f32 v[96:97], v[200:201], v[200:201], v[96:97]
	v_mul_f32_e32 v98, v201, v201
	v_lshlrev_b32_e32 v196, 16, v106
	v_and_b32_e32 v197, 0xffff0000, v106
	v_pk_add_f32 v[96:97], v[98:99], v[96:97] op_sel_hi:[0,1]
	v_pk_fma_f32 v[96:97], v[196:197], v[196:197], v[96:97]
	v_mul_f32_e32 v98, v197, v197
	v_lshlrev_b32_e32 v194, 16, v107
	v_and_b32_e32 v195, 0xffff0000, v107
	v_pk_add_f32 v[96:97], v[98:99], v[96:97] op_sel_hi:[0,1]
	v_pk_fma_f32 v[96:97], v[194:195], v[194:195], v[96:97]
	v_mul_f32_e32 v98, v195, v195
	s_waitcnt vmcnt(10)
	v_lshlrev_b32_e32 v192, 16, v166
	v_and_b32_e32 v193, 0xffff0000, v166
	v_pk_add_f32 v[96:97], v[98:99], v[96:97] op_sel_hi:[0,1]
	v_pk_fma_f32 v[96:97], v[192:193], v[192:193], v[96:97]
	v_mul_f32_e32 v98, v193, v193
	s_waitcnt vmcnt(8)
; __device__ __forceinline__ float bf_lo(unsigned w) { return __uint_as_float(w << 16); }
; __device__ __forceinline__ float bf_hi(unsigned w) { return __uint_as_float(w & 0xffff0000u); }
; __device__ __forceinline__ float xsum32(float v) { auto rr = __builtin_amdgcn_permlane32_swap(__float_as_uint(v), __float_as_uint(v), false, false); return __uint_as_float(rr[0]) + __uint_as_float(rr[1]); }
; __device__ __forceinline__ void mla_load_q(const bf16_t* qrow, int h, int pos, const float* qn, const float* rc, const float* rs, bf16x8 (&qf)[6]) {
;     float v[6][8]; float ss = 0.f;
; #pragma unroll
;     for (int ds = 0; ds < 6; ++ds) { const u32x4 w = *(const u32x4*)(qrow + 16 * ds + 8 * h);
;         v[ds][0] = bf_lo(w.x); v[ds][1] = bf_hi(w.x); v[ds][2] = bf_lo(w.y); v[ds][3] = bf_hi(w.y); v[ds][4] = bf_lo(w.z); v[ds][5] = bf_hi(w.z); v[ds][6] = bf_lo(w.w); v[ds][7] = bf_hi(w.w);
; #pragma unroll
;         for (int j = 0; j < 8; ++j) ss += v[ds][j] * v[ds][j]; }
;     ss = xsum32(ss);
	v_lshlrev_b32_e32 v152, 16, v191
	v_and_b32_e32 v153, 0xffff0000, v191
	v_lshlrev_b32_e32 v154, 16, v190
	v_and_b32_e32 v155, 0xffff0000, v190
	v_lshlrev_b32_e32 v190, 16, v167
	v_and_b32_e32 v191, 0xffff0000, v167
	v_pk_add_f32 v[96:97], v[98:99], v[96:97] op_sel_hi:[0,1]
	v_pk_fma_f32 v[96:97], v[190:191], v[190:191], v[96:97]
	v_mul_f32_e32 v98, v191, v191
	v_lshlrev_b32_e32 v186, 16, v168
	v_and_b32_e32 v187, 0xffff0000, v168
	v_pk_add_f32 v[96:97], v[98:99], v[96:97] op_sel_hi:[0,1]
	v_pk_fma_f32 v[96:97], v[186:187], v[186:187], v[96:97]
	v_mul_f32_e32 v98, v187, v187
	v_lshlrev_b32_e32 v184, 16, v169
	v_and_b32_e32 v185, 0xffff0000, v169
	v_pk_add_f32 v[96:97], v[98:99], v[96:97] op_sel_hi:[0,1]
	v_pk_fma_f32 v[96:97], v[184:185], v[184:185], v[96:97]
	v_mul_f32_e32 v98, v185, v185
	v_pk_add_f32 v[96:97], v[98:99], v[96:97] op_sel_hi:[0,1]
	v_pk_fma_f32 v[96:97], v[180:181], v[180:181], v[96:97]
	v_mul_f32_e32 v98, v181, v181
	v_pk_add_f32 v[96:97], v[98:99], v[96:97] op_sel_hi:[0,1]
	v_pk_fma_f32 v[96:97], v[178:179], v[178:179], v[96:97]
	v_mul_f32_e32 v98, v179, v179
	v_pk_add_f32 v[96:97], v[98:99], v[96:97] op_sel_hi:[0,1]
	v_pk_fma_f32 v[96:97], v[174:175], v[174:175], v[96:97]
	v_mul_f32_e32 v98, v175, v175
	v_lshlrev_b32_e32 v172, 16, v99
	v_and_b32_e32 v173, 0xffff0000, v99
	v_pk_add_f32 v[96:97], v[98:99], v[96:97] op_sel_hi:[0,1]
	v_pk_fma_f32 v[96:97], v[172:173], v[172:173], v[96:97]
	v_mul_f32_e32 v98, v173, v173
	v_lshlrev_b32_e32 v130, 16, v64
	v_and_b32_e32 v131, 0xffff0000, v64
	v_pk_add_f32 v[96:97], v[98:99], v[96:97] op_sel_hi:[0,1]
	v_pk_fma_f32 v[96:97], v[130:131], v[130:131], v[96:97]
	v_mul_f32_e32 v98, v131, v131
	v_lshlrev_b32_e32 v128, 16, v65
	v_and_b32_e32 v129, 0xffff0000, v65
	v_pk_add_f32 v[96:97], v[98:99], v[96:97] op_sel_hi:[0,1]
	v_pk_fma_f32 v[96:97], v[128:129], v[128:129], v[96:97]
	v_mul_f32_e32 v98, v129, v129
	v_lshlrev_b32_e32 v120, 16, v66
	v_and_b32_e32 v121, 0xffff0000, v66
	v_pk_add_f32 v[96:97], v[98:99], v[96:97] op_sel_hi:[0,1]
	v_pk_fma_f32 v[96:97], v[120:121], v[120:121], v[96:97]
	v_mul_f32_e32 v98, v121, v121
	v_lshlrev_b32_e32 v116, 16, v67
	v_and_b32_e32 v117, 0xffff0000, v67
	v_pk_add_f32 v[96:97], v[98:99], v[96:97] op_sel_hi:[0,1]
	v_pk_fma_f32 v[96:97], v[116:117], v[116:117], v[96:97]
	v_mul_f32_e32 v98, v117, v117
	v_lshlrev_b32_e32 v122, 16, v40
	v_and_b32_e32 v123, 0xffff0000, v40
	v_pk_add_f32 v[96:97], v[98:99], v[96:97] op_sel_hi:[0,1]
	v_pk_fma_f32 v[96:97], v[122:123], v[122:123], v[96:97]
	v_mul_f32_e32 v98, v123, v123
	v_lshlrev_b32_e32 v112, 16, v41
	v_and_b32_e32 v113, 0xffff0000, v41
	v_pk_add_f32 v[96:97], v[98:99], v[96:97] op_sel_hi:[0,1]
	v_pk_fma_f32 v[96:97], v[112:113], v[112:113], v[96:97]
	v_mul_f32_e32 v98, v113, v113
	v_lshlrev_b32_e32 v126, 16, v42
	v_and_b32_e32 v127, 0xffff0000, v42
	v_pk_add_f32 v[96:97], v[98:99], v[96:97] op_sel_hi:[0,1]
	v_pk_fma_f32 v[96:97], v[126:127], v[126:127], v[96:97]
	v_mul_f32_e32 v98, v127, v127
	v_lshlrev_b32_e32 v110, 16, v43
	v_and_b32_e32 v111, 0xffff0000, v43
	v_pk_add_f32 v[96:97], v[98:99], v[96:97] op_sel_hi:[0,1]
	v_pk_fma_f32 v[96:97], v[110:111], v[110:111], v[96:97]
	v_mul_f32_e32 v98, v111, v111
	v_lshlrev_b32_e32 v118, 16, v44
	v_and_b32_e32 v119, 0xffff0000, v44
	v_pk_add_f32 v[96:97], v[98:99], v[96:97] op_sel_hi:[0,1]
	v_pk_fma_f32 v[96:97], v[118:119], v[118:119], v[96:97]
	v_mul_f32_e32 v98, v119, v119
	v_lshlrev_b32_e32 v108, 16, v45
	v_and_b32_e32 v109, 0xffff0000, v45
	v_pk_add_f32 v[96:97], v[98:99], v[96:97] op_sel_hi:[0,1]
	v_pk_fma_f32 v[96:97], v[108:109], v[108:109], v[96:97]
	v_mul_f32_e32 v98, v109, v109
	v_lshlrev_b32_e32 v124, 16, v46
	v_and_b32_e32 v125, 0xffff0000, v46
	v_pk_add_f32 v[96:97], v[98:99], v[96:97] op_sel_hi:[0,1]
	v_pk_fma_f32 v[96:97], v[124:125], v[124:125], v[96:97]
	v_mul_f32_e32 v98, v125, v125
	v_and_b32_e32 v203, 0xffff0000, v80
	v_lshlrev_b32_e32 v114, 16, v47
	v_and_b32_e32 v115, 0xffff0000, v47
	v_pk_add_f32 v[96:97], v[98:99], v[96:97] op_sel_hi:[0,1]
	v_lshlrev_b32_e32 v202, 16, v80
	v_mul_f32_e32 v80, v203, v203
	v_lshlrev_b32_e32 v170, 16, v189
	v_and_b32_e32 v171, 0xffff0000, v189
	v_lshlrev_b32_e32 v176, 16, v188
	v_and_b32_e32 v177, 0xffff0000, v188
	v_lshlrev_b32_e32 v182, 16, v83
	v_and_b32_e32 v183, 0xffff0000, v83
	v_lshlrev_b32_e32 v188, 16, v82
	v_and_b32_e32 v189, 0xffff0000, v82
	v_lshlrev_b32_e32 v82, 16, v81
	v_and_b32_e32 v83, 0xffff0000, v81
	v_pk_fma_f32 v[96:97], v[114:115], v[114:115], v[96:97]
	v_mul_f32_e32 v98, v115, v115
	v_pk_fma_f32 v[80:81], v[202:203], v[202:203], v[80:81] op_sel_hi:[1,1,0]
	v_pk_add_f32 v[168:169], v[98:99], v[96:97] op_sel_hi:[0,1]
	v_pk_fma_f32 v[80:81], v[82:83], v[82:83], v[80:81]
	v_mul_f32_e32 v96, v83, v83
	v_pk_add_f32 v[80:81], v[96:97], v[80:81] op_sel_hi:[0,1]
	v_pk_fma_f32 v[80:81], v[188:189], v[188:189], v[80:81]
	v_mul_f32_e32 v96, v189, v189
	v_mov_b32_e32 v167, v206
	v_and_b32_e32 v85, 0xffff0000, v75
	v_lshlrev_b32_e32 v92, 16, v70
	v_and_b32_e32 v93, 0xffff0000, v70
	v_lshlrev_b32_e32 v86, 16, v74
	v_and_b32_e32 v87, 0xffff0000, v74
	v_lshlrev_b32_e32 v132, 16, v69
	v_and_b32_e32 v133, 0xffff0000, v69
	v_lshlrev_b32_e32 v90, 16, v73
	v_and_b32_e32 v91, 0xffff0000, v73
	v_lshlrev_b32_e32 v134, 16, v68
	v_and_b32_e32 v135, 0xffff0000, v68
	v_lshlrev_b32_e32 v94, 16, v72
	v_and_b32_e32 v95, 0xffff0000, v72
	v_lshlrev_b32_e32 v136, 16, v79
	v_and_b32_e32 v137, 0xffff0000, v79
	v_lshlrev_b32_e32 v138, 16, v78
	v_and_b32_e32 v139, 0xffff0000, v78
	v_lshlrev_b32_e32 v140, 16, v77
	v_and_b32_e32 v141, 0xffff0000, v77
	v_lshlrev_b32_e32 v142, 16, v76
	v_and_b32_e32 v143, 0xffff0000, v76
; __device__ __forceinline__ float bf_lo(unsigned w) { return __uint_as_float(w << 16); }
; __device__ __forceinline__ float bf_hi(unsigned w) { return __uint_as_float(w & 0xffff0000u); }
; __device__ __forceinline__ float xsum32(float v) { auto rr = __builtin_amdgcn_permlane32_swap(__float_as_uint(v), __float_as_uint(v), false, false); return __uint_as_float(rr[0]) + __uint_as_float(rr[1]); }
; __device__ __forceinline__ void mla_load_q(const bf16_t* qrow, int h, int pos, const float* qn, const float* rc, const float* rs, bf16x8 (&qf)[6]) {
;     float v[6][8]; float ss = 0.f;
; #pragma unroll
;     for (int ds = 0; ds < 6; ++ds) { const u32x4 w = *(const u32x4*)(qrow + 16 * ds + 8 * h);
;         v[ds][0] = bf_lo(w.x); v[ds][1] = bf_hi(w.x); v[ds][2] = bf_lo(w.y); v[ds][3] = bf_hi(w.y); v[ds][4] = bf_lo(w.z); v[ds][5] = bf_hi(w.z); v[ds][6] = bf_lo(w.w); v[ds][7] = bf_hi(w.w);
; #pragma unroll
;         for (int j = 0; j < 8; ++j) ss += v[ds][j] * v[ds][j]; }
;     ss = xsum32(ss);
	global_load_dwordx4 v[40:43], v[156:157], off offset:144
	global_load_dwordx4 v[44:47], v[156:157], off offset:128
	global_load_dwordx4 v[64:67], v[156:157], off offset:80
	global_load_dwordx4 v[68:71], v[156:157], off offset:64
	global_load_dwordx4 v[72:75], v[156:157], off offset:16
	global_load_dwordx4 v[76:79], v[156:157], off
	v_pk_add_f32 v[80:81], v[96:97], v[80:81] op_sel_hi:[0,1]
	v_lshlrev_b32_e32 v150, 16, v100
	v_mul_hi_i32 v96, v167, s33
	v_lshrrev_b32_e32 v97, 31, v96
	v_ashrrev_i32_e32 v96, 1, v96
	v_add_u32_e32 v96, v96, v97
	v_mul_lo_u32 v97, v96, 12
	v_sub_u32_e32 v97, v167, v97
	v_mul_lo_u32 v98, v96, s35
	v_lshl_add_u32 v159, v97, 4, v98
	v_lshlrev_b32_e32 v96, 4, v96
	v_sub_u32_e32 v160, v159, v96
	v_and_b32_e32 v151, 0xffff0000, v100
	v_pk_fma_f32 v[80:81], v[182:183], v[182:183], v[80:81]
	v_mul_f32_e32 v100, v183, v183
	v_pk_add_f32 v[80:81], v[100:101], v[80:81] op_sel_hi:[0,1]
	v_pk_fma_f32 v[80:81], v[176:177], v[176:177], v[80:81]
	v_mul_f32_e32 v100, v177, v177
	v_pk_add_f32 v[80:81], v[100:101], v[80:81] op_sel_hi:[0,1]
	v_pk_fma_f32 v[80:81], v[170:171], v[170:171], v[80:81]
	v_mul_f32_e32 v100, v171, v171
	v_pk_add_f32 v[80:81], v[100:101], v[80:81] op_sel_hi:[0,1]
	v_pk_fma_f32 v[80:81], v[154:155], v[154:155], v[80:81]
	v_mul_f32_e32 v100, v155, v155
	v_pk_add_f32 v[80:81], v[100:101], v[80:81] op_sel_hi:[0,1]
	v_pk_fma_f32 v[80:81], v[152:153], v[152:153], v[80:81]
	v_mul_f32_e32 v100, v153, v153
	v_pk_add_f32 v[80:81], v[100:101], v[80:81] op_sel_hi:[0,1]
	v_pk_fma_f32 v[80:81], v[150:151], v[150:151], v[80:81]
	v_mul_f32_e32 v100, v151, v151
	v_lshlrev_b32_e32 v148, 16, v101
	v_and_b32_e32 v149, 0xffff0000, v101
	v_pk_add_f32 v[80:81], v[100:101], v[80:81] op_sel_hi:[0,1]
	v_pk_fma_f32 v[80:81], v[148:149], v[148:149], v[80:81]
	v_mul_f32_e32 v100, v149, v149
	v_lshlrev_b32_e32 v146, 16, v102
	v_and_b32_e32 v147, 0xffff0000, v102
	v_pk_add_f32 v[80:81], v[100:101], v[80:81] op_sel_hi:[0,1]
	v_pk_fma_f32 v[80:81], v[146:147], v[146:147], v[80:81]
	v_mul_f32_e32 v100, v147, v147
	v_lshlrev_b32_e32 v144, 16, v103
	v_and_b32_e32 v145, 0xffff0000, v103
	v_pk_add_f32 v[80:81], v[100:101], v[80:81] op_sel_hi:[0,1]
	v_pk_fma_f32 v[80:81], v[144:145], v[144:145], v[80:81]
	v_mul_f32_e32 v100, v145, v145
	v_pk_add_f32 v[80:81], v[100:101], v[80:81] op_sel_hi:[0,1]
	v_pk_fma_f32 v[80:81], v[142:143], v[142:143], v[80:81]
	v_mul_f32_e32 v100, v143, v143
	v_pk_add_f32 v[80:81], v[100:101], v[80:81] op_sel_hi:[0,1]
	v_pk_fma_f32 v[80:81], v[140:141], v[140:141], v[80:81]
	v_mul_f32_e32 v100, v141, v141
	v_pk_add_f32 v[80:81], v[100:101], v[80:81] op_sel_hi:[0,1]
	v_pk_fma_f32 v[80:81], v[138:139], v[138:139], v[80:81]
	v_mul_f32_e32 v100, v139, v139
	v_pk_add_f32 v[80:81], v[100:101], v[80:81] op_sel_hi:[0,1]
	v_pk_fma_f32 v[80:81], v[136:137], v[136:137], v[80:81]
	v_mul_f32_e32 v100, v137, v137
	v_pk_add_f32 v[80:81], v[100:101], v[80:81] op_sel_hi:[0,1]
	v_pk_fma_f32 v[80:81], v[134:135], v[134:135], v[80:81]
	v_mul_f32_e32 v100, v135, v135
	v_pk_add_f32 v[80:81], v[100:101], v[80:81] op_sel_hi:[0,1]
	v_pk_fma_f32 v[80:81], v[132:133], v[132:133], v[80:81]
	v_mul_f32_e32 v100, v133, v133
	v_pk_add_f32 v[80:81], v[100:101], v[80:81] op_sel_hi:[0,1]
	v_pk_fma_f32 v[80:81], v[92:93], v[92:93], v[80:81]
	v_mul_f32_e32 v100, v93, v93
	v_pk_add_f32 v[80:81], v[100:101], v[80:81] op_sel_hi:[0,1]
	v_pk_fma_f32 v[80:81], v[88:89], v[88:89], v[80:81]
	v_mul_f32_e32 v100, v89, v89
	v_pk_add_f32 v[80:81], v[100:101], v[80:81] op_sel_hi:[0,1]
	v_pk_fma_f32 v[80:81], v[94:95], v[94:95], v[80:81]
	v_mul_f32_e32 v100, v95, v95
	v_pk_add_f32 v[80:81], v[100:101], v[80:81] op_sel_hi:[0,1]
	v_pk_fma_f32 v[80:81], v[90:91], v[90:91], v[80:81]
	v_mul_f32_e32 v100, v91, v91
	v_pk_add_f32 v[80:81], v[100:101], v[80:81] op_sel_hi:[0,1]
	v_pk_fma_f32 v[80:81], v[86:87], v[86:87], v[80:81]
	v_mul_f32_e32 v100, v87, v87
	v_pk_add_f32 v[80:81], v[100:101], v[80:81] op_sel_hi:[0,1]
	v_pk_fma_f32 v[80:81], v[84:85], v[84:85], v[80:81]
	v_mul_f32_e32 v100, v85, v85
	v_pk_add_f32 v[80:81], v[100:101], v[80:81] op_sel_hi:[0,1]
	v_add_u32_e32 v81, 0x200, v167
	v_mul_hi_i32 v100, v81, s33
	v_lshrrev_b32_e32 v101, 31, v100
	v_ashrrev_i32_e32 v100, 1, v100
	v_add_u32_e32 v205, v100, v101
	v_mul_lo_u32 v100, v205, 12
	v_mov_b32_e32 v169, v168
	v_mov_b32_e32 v214, v80
	v_sub_u32_e32 v81, v81, v100
	v_mul_lo_u32 v100, v205, s29
	v_permlane32_swap_b32_e32 v168, v169
	v_permlane32_swap_b32_e32 v80, v214
	v_lshl_add_u32 v166, v81, 4, v100
	v_cmp_gt_i32_e64 s[0:1], s34, v167
	v_mov_b32_e32 v100, v161
	v_mov_b32_e32 v101, v161
	v_mov_b32_e32 v102, v161
	v_mov_b32_e32 v103, v161
	s_and_saveexec_b64 s[22:23], s[0:1]
	s_cbranch_execz .LBB0_1122
; __device__ __forceinline__ unsigned pk2(float lo, float hi) { f32x2_t v = {lo, hi}; bf16x2_t b = __builtin_convertvector(v, bf16x2_t); return __builtin_bit_cast(unsigned, b); }
; __device__ __forceinline__ void mla_load_q(const bf16_t* qrow, int h, int pos, const float* qn, const float* rc, const float* rs, bf16x8 (&qf)[6]) {
;     ...
;     const float rr = __builtin_amdgcn_rsqf(ss * (1.0f / 96.0f) + EPS) * QSCALE_C;
; #pragma unroll
;     for (int ds = 0; ds < 6; ++ds)
; #pragma unroll
;         for (int j = 0; j < 8; ++j) v[ds][j] *= rr * qn[16 * ds + 8 * h + j];
; #pragma unroll
;     for (int j = 0; j < 8; ++j) { const float c = rc[pos * 16 + 8 * h + j], s = rs[pos * 16 + 8 * h + j]; const float a = v[4][j], b = v[5][j]; v[4][j] = a * c - b * s; v[5][j] = b * c + a * s; }
; #pragma unroll
;     for (int ds = 0; ds < 6; ++ds) { u32x4 p; p.x = pk2(v[ds][0], v[ds][1]); p.y = pk2(v[ds][2], v[ds][3]); p.z = pk2(v[ds][4], v[ds][5]); p.w = pk2(v[ds][6], v[ds][7]); qf[ds] = __builtin_bit_cast(bf16x8, p); }
.LBB0_1122:
	s_or_b64 exec, exec, s[22:23]
	s_lshl_b64 s[20:21], s[20:21], 7
	v_and_b32_e32 v213, 7, v167
	s_add_u32 s20, s12, s20
	v_ashrrev_i32_e32 v81, 3, v167
	v_lshlrev_b32_e32 v104, 4, v213
	s_addc_u32 s21, s13, s21
	v_lshl_or_b32 v204, v81, 7, v104
	v_lshl_add_u32 v212, v205, 4, v166
	v_add_u32_e32 v205, 0, v159
	s_waitcnt vmcnt(0)
	ds_write_b128 v205, v[248:251]
	s_and_saveexec_b64 s[22:23], s[0:1]
	v_add_u32_e32 v205, 0, v212
	ds_write_b128 v205, v[240:243]
	s_or_b64 exec, exec, s[22:23]
	v_add_f32_e32 v168, v168, v169
	v_fmamk_f32 v168, v168, 0x3c2aaaab, v209
	v_rsq_f32_e32 v215, v168
	v_mov_b32_e32 v205, v161
	v_lshl_add_u64 v[168:169], s[20:21], 0, v[204:205]
	s_mov_b32 s40, 0
	v_mul_f32_e32 v204, 0x3e16c740, v215
	v_pk_mul_f32 v[216:217], v[204:205], v[10:11] op_sel_hi:[0,1]
	v_pk_mul_f32 v[218:219], v[204:205], v[2:3] op_sel_hi:[0,1]
	v_pk_mul_f32 v[110:111], v[216:217], v[110:111]
	v_pk_mul_f32 v[114:115], v[218:219], v[114:115]
	s_mov_b32 s4, s40
	v_pk_mul_f32 v[216:217], v[114:115], v[62:63]
	v_pk_mul_f32 v[62:63], v[110:111], v[62:63]
	v_pk_fma_f32 v[216:217], v[110:111], v[58:59], v[216:217] neg_lo:[0,0,1] neg_hi:[0,0,1]
	v_pk_fma_f32 v[58:59], v[114:115], v[58:59], v[62:63]
	v_pk_mul_f32 v[62:63], v[204:205], v[0:1] op_sel_hi:[0,1]
	v_cvt_pk_bf16_f32 v115, v58, v59
	v_pk_mul_f32 v[58:59], v[204:205], v[8:9] op_sel_hi:[0,1]
	v_pk_mul_f32 v[62:63], v[62:63], v[124:125]
	v_pk_mul_f32 v[58:59], v[58:59], v[126:127]
	v_pk_mul_f32 v[124:125], v[62:63], v[60:61]
	v_cvt_pk_bf16_f32 v111, v216, v217
	v_pk_fma_f32 v[124:125], v[58:59], v[56:57], v[124:125] neg_lo:[0,0,1] neg_hi:[0,0,1]
	v_pk_mul_f32 v[58:59], v[58:59], v[60:61]
	v_cvt_pk_bf16_f32 v110, v124, v125
	v_pk_fma_f32 v[56:57], v[62:63], v[56:57], v[58:59]
	v_pk_mul_f32 v[58:59], v[204:205], v[6:7] op_sel_hi:[0,1]
	v_cvt_pk_bf16_f32 v114, v56, v57
	v_pk_mul_f32 v[56:57], v[204:205], v[14:15] op_sel_hi:[0,1]
	v_pk_mul_f32 v[56:57], v[56:57], v[112:113]
	v_pk_mul_f32 v[58:59], v[58:59], v[108:109]
	s_nop 0
	v_pk_mul_f32 v[60:61], v[58:59], v[54:55]
	v_pk_mul_f32 v[54:55], v[56:57], v[54:55]
	v_pk_fma_f32 v[60:61], v[56:57], v[50:51], v[60:61] neg_lo:[0,0,1] neg_hi:[0,0,1]
	v_pk_fma_f32 v[50:51], v[58:59], v[50:51], v[54:55]
	v_pk_mul_f32 v[54:55], v[204:205], v[4:5] op_sel_hi:[0,1]
	v_cvt_pk_bf16_f32 v113, v50, v51
	v_pk_mul_f32 v[50:51], v[204:205], v[12:13] op_sel_hi:[0,1]
	v_pk_mul_f32 v[54:55], v[54:55], v[118:119]
	v_pk_mul_f32 v[50:51], v[50:51], v[122:123]
	v_pk_mul_f32 v[56:57], v[54:55], v[52:53]
	v_cvt_pk_bf16_f32 v109, v60, v61
	v_pk_fma_f32 v[56:57], v[50:51], v[48:49], v[56:57] neg_lo:[0,0,1] neg_hi:[0,0,1]
	v_pk_mul_f32 v[50:51], v[50:51], v[52:53]
	v_cvt_pk_bf16_f32 v108, v56, v57
	v_pk_fma_f32 v[48:49], v[54:55], v[48:49], v[50:51]
	s_nop 0
	v_cvt_pk_bf16_f32 v112, v48, v49
	v_pk_mul_f32 v[48:49], v[204:205], v[34:35] op_sel_hi:[0,1]
	v_pk_mul_f32 v[48:49], v[48:49], v[116:117]
	s_nop 0
	v_cvt_pk_bf16_f32 v119, v48, v49
	v_pk_mul_f32 v[48:49], v[204:205], v[32:33] op_sel_hi:[0,1]
	v_pk_mul_f32 v[48:49], v[48:49], v[120:121]
	s_nop 0
	v_cvt_pk_bf16_f32 v118, v48, v49
	v_pk_mul_f32 v[48:49], v[204:205], v[38:39] op_sel_hi:[0,1]
	v_pk_mul_f32 v[48:49], v[48:49], v[128:129]
	s_nop 0
	v_cvt_pk_bf16_f32 v117, v48, v49
	v_pk_mul_f32 v[48:49], v[204:205], v[36:37] op_sel_hi:[0,1]
	v_pk_mul_f32 v[48:49], v[48:49], v[130:131]
	s_nop 0
	v_cvt_pk_bf16_f32 v116, v48, v49
	v_pk_mul_f32 v[48:49], v[204:205], v[42:43] op_sel_hi:[0,1]
	v_pk_mul_f32 v[48:49], v[48:49], v[172:173]
	s_nop 0
	v_cvt_pk_bf16_f32 v123, v48, v49
	v_pk_mul_f32 v[48:49], v[204:205], v[40:41] op_sel_hi:[0,1]
	v_pk_mul_f32 v[48:49], v[48:49], v[174:175]
	s_nop 0
	v_cvt_pk_bf16_f32 v122, v48, v49
	v_pk_mul_f32 v[48:49], v[204:205], v[46:47] op_sel_hi:[0,1]
	v_pk_mul_f32 v[48:49], v[48:49], v[178:179]
	s_nop 0
	v_cvt_pk_bf16_f32 v121, v48, v49
	v_pk_mul_f32 v[48:49], v[204:205], v[44:45] op_sel_hi:[0,1]
	v_pk_mul_f32 v[48:49], v[48:49], v[180:181]
	s_nop 0
	v_cvt_pk_bf16_f32 v120, v48, v49
	v_pk_mul_f32 v[48:49], v[204:205], v[66:67] op_sel_hi:[0,1]
	v_pk_mul_f32 v[48:49], v[48:49], v[184:185]
	s_nop 0
	v_cvt_pk_bf16_f32 v127, v48, v49
	v_pk_mul_f32 v[48:49], v[204:205], v[64:65] op_sel_hi:[0,1]
	v_pk_mul_f32 v[48:49], v[48:49], v[186:187]
	s_nop 0
	v_cvt_pk_bf16_f32 v126, v48, v49
	v_pk_mul_f32 v[48:49], v[204:205], v[70:71] op_sel_hi:[0,1]
	v_pk_mul_f32 v[48:49], v[48:49], v[190:191]
	s_nop 0
	v_cvt_pk_bf16_f32 v125, v48, v49
	v_pk_mul_f32 v[48:49], v[204:205], v[68:69] op_sel_hi:[0,1]
	v_pk_mul_f32 v[48:49], v[48:49], v[192:193]
	s_nop 0
	v_cvt_pk_bf16_f32 v124, v48, v49
	v_pk_mul_f32 v[48:49], v[204:205], v[74:75] op_sel_hi:[0,1]
	v_pk_mul_f32 v[48:49], v[48:49], v[194:195]
	s_nop 0
	v_cvt_pk_bf16_f32 v131, v48, v49
	v_pk_mul_f32 v[48:49], v[72:73], v[204:205] op_sel_hi:[1,0]
	s_nop 0
	v_pk_mul_f32 v[48:49], v[48:49], v[196:197]
	s_nop 0
	v_cvt_pk_bf16_f32 v130, v48, v49
	v_pk_mul_f32 v[48:49], v[78:79], v[204:205] op_sel_hi:[1,0]
	s_nop 0
	v_pk_mul_f32 v[48:49], v[48:49], v[200:201]
	s_nop 0
	v_cvt_pk_bf16_f32 v129, v48, v49
	v_add_f32_e32 v48, v80, v214
	v_fmamk_f32 v48, v48, 0x3c2aaaab, v209
	v_rsq_f32_e32 v50, v48
	v_pk_mul_f32 v[48:49], v[76:77], v[204:205] op_sel_hi:[1,0]
	s_nop 0
	v_pk_mul_f32 v[48:49], v[48:49], v[198:199]
	s_nop 0
	v_cvt_pk_bf16_f32 v128, v48, v49
	v_mul_f32_e32 v48, 0x3e16c740, v50
	v_pk_mul_f32 v[4:5], v[4:5], v[48:49] op_sel_hi:[1,0]
	v_pk_mul_f32 v[12:13], v[12:13], v[48:49] op_sel_hi:[1,0]
	v_pk_mul_f32 v[4:5], v[4:5], v[94:95]
	v_pk_mul_f32 v[6:7], v[6:7], v[48:49] op_sel_hi:[1,0]
	v_pk_mul_f32 v[50:51], v[76:77], v[48:49] op_sel_hi:[1,0]
; __device__ __forceinline__ unsigned pk2(float lo, float hi) { f32x2_t v = {lo, hi}; bf16x2_t b = __builtin_convertvector(v, bf16x2_t); return __builtin_bit_cast(unsigned, b); }
; #define A64_GLOAD(t) do { A64_IDX(); const char* Kt = (const char*)(Kg + (size_t)(t) * 64 * ldk); const char* Vt = (const char*)(Vg + (size_t)(t) * 64 * ldv); \
;         kreg0 = *(const u32x4*)(Kt + (unsigned)(kk0 * ldk + kc0 * 8) * 2u); if (k2) kreg1 = *(const u32x4*)(Kt + (unsigned)(kk1 * ldk + kc1 * 8) * 2u); vreg = *(const u32x4*)(Vt + (unsigned)(vk * ldv + vc * 8) * 2u); } while (0)
; #define A64_LWRITE(bo) do { A64_IDX(); *(LAS u32x4*)(lds + (bo) + kk0 * KP + kc0 * 16) = kreg0; if (k2) *(LAS u32x4*)(lds + (bo) + kk1 * KP + kc1 * 16) = kreg1; \
;         *(LAS u32x4*)(lds + (bo) + KBYTES + (vc >> 2) * 4096 + vk * 64 + (vc & 3) * 16) = vreg; } while (0)
; #define A64_KREAD(bo, half) do { _Pragma("unroll") for (int ds = 0; ds < NDS; ++ds) kf[ds] = *(const LAS bf16x8*)(lds + (bo) + kfr + (half) * 32 * KP + ds * 32); } while (0)
; template <int DQK>
; __device__ __forceinline__ void attn_unit64p(LAS char* lds, const bf16x8 (&qa)[DQK / 16], const bf16x8 (&qb)[DQK / 16],
;                                              const bf16_t* Kg, int ldk, const bf16_t* Vg, int ldv, int nt, bf16_t* Obase, int ldo, int ogb_off) {
;     ...
;     A64_GLOAD(0); A64_LWRITE(0);
;     __syncthreads();
;     if (nt > 1) A64_GLOAD(1);
;     A64_KREAD(0, 0);
; __device__ __forceinline__ void mla_load_q(const bf16_t* qrow, int h, int pos, const float* qn, const float* rc, const float* rs, bf16x8 (&qf)[6]) {
;     ...
;     const float rr = __builtin_amdgcn_rsqf(ss * (1.0f / 96.0f) + EPS) * QSCALE_C;
; #pragma unroll
;     for (int ds = 0; ds < 6; ++ds)
; #pragma unroll
;         for (int j = 0; j < 8; ++j) v[ds][j] *= rr * qn[16 * ds + 8 * h + j];
; #pragma unroll
;     for (int j = 0; j < 8; ++j) { const float c = rc[pos * 16 + 8 * h + j], s = rs[pos * 16 + 8 * h + j]; const float a = v[4][j], b = v[5][j]; v[4][j] = a * c - b * s; v[5][j] = b * c + a * s; }
; #pragma unroll
;     for (int ds = 0; ds < 6; ++ds) { u32x4 p; p.x = pk2(v[ds][0], v[ds][1]); p.y = pk2(v[ds][2], v[ds][3]); p.z = pk2(v[ds][4], v[ds][5]); p.w = pk2(v[ds][6], v[ds][7]); qf[ds] = __builtin_bit_cast(bf16x8, p); }
	v_pk_mul_f32 v[52:53], v[78:79], v[48:49] op_sel_hi:[1,0]
	v_pk_mul_f32 v[54:55], v[72:73], v[48:49] op_sel_hi:[1,0]
	v_pk_mul_f32 v[56:57], v[74:75], v[48:49] op_sel_hi:[1,0]
	v_pk_mul_f32 v[58:59], v[68:69], v[48:49] op_sel_hi:[1,0]
	v_pk_mul_f32 v[60:61], v[70:71], v[48:49] op_sel_hi:[1,0]
	v_pk_mul_f32 v[62:63], v[64:65], v[48:49] op_sel_hi:[1,0]
	v_pk_mul_f32 v[64:65], v[66:67], v[48:49] op_sel_hi:[1,0]
	v_pk_mul_f32 v[44:45], v[44:45], v[48:49] op_sel_hi:[1,0]
	v_pk_mul_f32 v[46:47], v[46:47], v[48:49] op_sel_hi:[1,0]
	v_pk_mul_f32 v[40:41], v[40:41], v[48:49] op_sel_hi:[1,0]
	v_pk_mul_f32 v[42:43], v[42:43], v[48:49] op_sel_hi:[1,0]
	v_pk_mul_f32 v[36:37], v[36:37], v[48:49] op_sel_hi:[1,0]
	v_pk_mul_f32 v[38:39], v[38:39], v[48:49] op_sel_hi:[1,0]
	v_pk_mul_f32 v[32:33], v[32:33], v[48:49] op_sel_hi:[1,0]
	v_pk_mul_f32 v[34:35], v[34:35], v[48:49] op_sel_hi:[1,0]
	v_pk_mul_f32 v[12:13], v[12:13], v[134:135]
	v_pk_mul_f32 v[14:15], v[14:15], v[48:49] op_sel_hi:[1,0]
	v_pk_mul_f32 v[8:9], v[8:9], v[48:49] op_sel_hi:[1,0]
	v_pk_mul_f32 v[10:11], v[10:11], v[48:49] op_sel_hi:[1,0]
	v_pk_mul_f32 v[6:7], v[6:7], v[90:91]
	v_pk_mul_f32 v[0:1], v[0:1], v[48:49] op_sel_hi:[1,0]
	v_pk_mul_f32 v[2:3], v[2:3], v[48:49] op_sel_hi:[1,0]
	v_pk_mul_f32 v[48:49], v[28:29], v[4:5]
	v_pk_mul_f32 v[4:5], v[24:25], v[4:5]
	v_pk_mul_f32 v[14:15], v[14:15], v[132:133]
	v_pk_mul_f32 v[0:1], v[0:1], v[86:87]
	v_pk_fma_f32 v[48:49], v[24:25], v[12:13], v[48:49] neg_lo:[0,0,1] neg_hi:[0,0,1]
	v_pk_fma_f32 v[4:5], v[28:29], v[12:13], v[4:5]
	v_pk_mul_f32 v[12:13], v[30:31], v[6:7]
	v_pk_mul_f32 v[6:7], v[26:27], v[6:7]
	v_pk_mul_f32 v[8:9], v[8:9], v[92:93]
	v_pk_fma_f32 v[12:13], v[26:27], v[14:15], v[12:13] neg_lo:[0,0,1] neg_hi:[0,0,1]
	v_pk_fma_f32 v[6:7], v[30:31], v[14:15], v[6:7]
	v_pk_mul_f32 v[14:15], v[0:1], v[20:21]
	v_pk_mul_f32 v[2:3], v[2:3], v[84:85]
	v_pk_fma_f32 v[14:15], v[8:9], v[16:17], v[14:15] neg_lo:[0,0,1] neg_hi:[0,0,1]
	v_pk_mul_f32 v[8:9], v[8:9], v[20:21]
	v_pk_mul_f32 v[10:11], v[10:11], v[88:89]
	v_pk_fma_f32 v[0:1], v[16:17], v[0:1], v[8:9]
	v_pk_mul_f32 v[8:9], v[2:3], v[22:23]
	v_pk_mul_f32 v[62:63], v[62:63], v[154:155]
	v_pk_fma_f32 v[8:9], v[10:11], v[18:19], v[8:9] neg_lo:[0,0,1] neg_hi:[0,0,1]
	v_pk_mul_f32 v[10:11], v[10:11], v[22:23]
	v_cvt_pk_bf16_f32 v154, v0, v1
	v_pk_fma_f32 v[2:3], v[2:3], v[18:19], v[10:11]
	v_and_b32_e32 v0, 31, v167
	v_pk_mul_f32 v[64:65], v[64:65], v[152:153]
	v_cvt_pk_bf16_f32 v152, v4, v5
	v_cvt_pk_bf16_f32 v155, v2, v3
	v_lshlrev_b32_e32 v3, 4, v167
	v_mul_u32_u24_e32 v175, 0xd0, v0
	v_and_b32_e32 v0, 16, v167
	v_lshlrev_b32_e32 v5, 2, v167
	v_lshlrev_b32_e32 v2, 10, v213
	v_and_b32_e32 v3, 48, v3
	v_and_or_b32 v0, v5, 12, v0
	v_bfe_u32 v1, v167, 5, 1
	v_and_b32_e32 v2, 0x1000, v2
	v_lshlrev_b32_e32 v178, 1, v0
	v_lshl_or_b32 v0, v81, 6, v3
	v_pk_mul_f32 v[46:47], v[46:47], v[148:149]
	v_pk_mul_f32 v[32:33], v[32:33], v[138:139]
	v_lshrrev_b32_e32 v4, 2, v167
	v_lshlrev_b32_e32 v174, 2, v1
	v_add_u32_e32 v179, v0, v2
	v_pk_mul_f32 v[50:51], v[50:51], v[202:203]
	v_pk_mul_f32 v[52:53], v[52:53], v[82:83]
	v_pk_mul_f32 v[54:55], v[54:55], v[188:189]
	v_pk_mul_f32 v[56:57], v[56:57], v[182:183]
	v_pk_mul_f32 v[58:59], v[58:59], v[176:177]
	v_pk_mul_f32 v[60:61], v[60:61], v[170:171]
	v_pk_mul_f32 v[44:45], v[44:45], v[150:151]
	v_pk_mul_f32 v[40:41], v[40:41], v[146:147]
	v_pk_mul_f32 v[42:43], v[42:43], v[144:145]
	v_pk_mul_f32 v[36:37], v[36:37], v[142:143]
	v_pk_mul_f32 v[38:39], v[38:39], v[140:141]
	v_pk_mul_f32 v[34:35], v[34:35], v[136:137]
	v_cvt_pk_bf16_f32 v141, v46, v47
	v_cvt_pk_bf16_f32 v146, v32, v33
	v_and_or_b32 v4, v4, 3, v174
	v_add_u32_e32 v0, 0, v179
	v_mov_b32_e32 v32, v161
	v_mov_b32_e32 v33, v161
	v_mov_b32_e32 v46, v161
	v_mov_b32_e32 v47, v161
	v_cvt_pk_bf16_f32 v132, v50, v51
	v_cvt_pk_bf16_f32 v133, v52, v53
	v_cvt_pk_bf16_f32 v134, v54, v55
	v_cvt_pk_bf16_f32 v135, v56, v57
	v_cvt_pk_bf16_f32 v136, v58, v59
	v_cvt_pk_bf16_f32 v137, v60, v61
	v_cvt_pk_bf16_f32 v138, v62, v63
	v_cvt_pk_bf16_f32 v140, v44, v45
	v_cvt_pk_bf16_f32 v142, v40, v41
	v_cvt_pk_bf16_f32 v143, v42, v43
	v_cvt_pk_bf16_f32 v144, v36, v37
	v_cvt_pk_bf16_f32 v145, v38, v39
	v_cvt_pk_bf16_f32 v147, v34, v35
	v_cvt_pk_bf16_f32 v148, v48, v49
	v_cvt_pk_bf16_f32 v149, v12, v13
	v_cvt_pk_bf16_f32 v150, v14, v15
	v_cvt_pk_bf16_f32 v151, v8, v9
	v_cvt_pk_bf16_f32 v153, v6, v7
	v_lshlrev_b32_e32 v176, 4, v1
	v_lshlrev_b32_e32 v177, 6, v4
	s_waitcnt vmcnt(0)
	ds_write_b128 v0, v[252:255] offset:13312
	v_mov_b32_e32 v170, v161
	v_mov_b32_e32 v171, v161
	v_mov_b32_e32 v34, v161
	v_mov_b32_e32 v35, v161
	v_mov_b32_e32 v36, v161
	v_mov_b32_e32 v37, v161
	v_mov_b32_e32 v38, v161
	v_mov_b32_e32 v39, v161
	v_mov_b32_e32 v40, v161
	v_mov_b32_e32 v41, v161
	v_mov_b32_e32 v42, v161
	v_mov_b32_e32 v43, v161
	v_mov_b32_e32 v44, v161
	v_mov_b32_e32 v45, v161
	v_mov_b64_e32 v[62:63], v[46:47]
	v_mov_b64_e32 v[16:17], v[32:33]
	v_mov_b64_e32 v[0:1], v[32:33]
	v_cvt_pk_bf16_f32 v139, v64, v65
	v_mov_b32_e32 v167, v161
	v_mov_b64_e32 v[60:61], v[44:45]
	v_mov_b64_e32 v[58:59], v[42:43]
	v_mov_b64_e32 v[56:57], v[40:41]
	v_mov_b64_e32 v[54:55], v[38:39]
	v_mov_b64_e32 v[52:53], v[36:37]
	v_mov_b64_e32 v[50:51], v[34:35]
	v_mov_b64_e32 v[48:49], v[32:33]
	v_mov_b64_e32 v[18:19], v[34:35]
	v_mov_b64_e32 v[20:21], v[36:37]
	v_mov_b64_e32 v[22:23], v[38:39]
	v_mov_b64_e32 v[24:25], v[40:41]
	v_mov_b64_e32 v[26:27], v[42:43]
	v_mov_b64_e32 v[28:29], v[44:45]
	v_mov_b64_e32 v[30:31], v[46:47]
	v_mov_b64_e32 v[2:3], v[34:35]
	v_mov_b64_e32 v[4:5], v[36:37]
	v_mov_b64_e32 v[6:7], v[38:39]
	v_mov_b64_e32 v[8:9], v[40:41]
	v_mov_b64_e32 v[10:11], v[42:43]
	v_mov_b64_e32 v[12:13], v[44:45]
	v_mov_b64_e32 v[14:15], v[46:47]
	v_mov_b64_e32 v[172:173], v[170:171]
	s_waitcnt lgkmcnt(0)
	s_barrier
	s_branch .LBB0_1127
